# mla_post: rope-key loads also hoisted to the top of the row iteration
# baseline (speedup 1.0000x reference)
.LBB0_2254:
	v_lshl_add_u64 v[0:1], s[50:51], 0, v[22:23]
	v_add_co_u32_e32 v0, vcc, 0xe000000, v0
	s_add_i32 s12, s18, 0xffff8000
	s_nop 0
	v_addc_co_u32_e32 v1, vcc, 0, v1, vcc
	global_load_dwordx2 v[2:3], v[0:1], off
	global_load_dwordx2 v[34:35], v[0:1], off offset:512
	global_load_dwordx2 v[36:37], v[0:1], off offset:1024
	global_load_dwordx2 v[38:39], v[6:7], off
	v_lshl_add_u64 v[60:61], s[50:51], 0, v[20:21]
	global_load_dwordx2 v[52:53], v[6:7], off offset:512
	global_load_dwordx2 v[54:55], v[6:7], off offset:1024
	global_load_dwordx4 v[56:59], v[60:61], off
	global_load_dwordx4 v[64:67], v[8:9], off
	s_and_b32 s98, s18, 63
	s_and_b32 s99, s18, 0x1fff
	s_or_b32 s98, s98, 0x400
	s_cmp_lt_i32 s18, 0x8000
	s_cselect_b32 s98, s99, s98
	s_lshl_b32 s98, s98, 8
	s_mov_b32 s99, s13
	v_lshl_add_u64 v[62:63], v[12:13], 0, s[98:99]
	v_lshl_add_u64 v[68:69], s[50:51], 0, v[18:19]
	s_nop 0
	v_add_co_u32_e32 v68, vcc, 0xe000000, v68
	s_nop 1
	v_addc_co_u32_e32 v69, vcc, 0, v69, vcc
	s_and_saveexec_b64 s[100:101], s[6:7]
	global_load_dwordx2 v[70:71], v[62:63], off
	global_load_dword v72, v[68:69], off offset:2688
	global_load_dword v73, v[68:69], off offset:2560
	s_or_b64 exec, exec, s[100:101]
	s_cmp_lt_i32 s18, 0x8000
	s_cselect_b64 s[26:27], -1, 0
	s_mov_b64 s[20:21], s[18:19]
	s_waitcnt vmcnt(7) lgkmcnt(0)
	v_pk_mul_f32 v[0:1], v[2:3], v[2:3]
	v_pk_mul_f32 v[40:41], v[34:35], v[34:35]
	v_pk_mul_f32 v[42:43], v[36:37], v[36:37]
	v_add_f32_e32 v40, v40, v41
	v_add_f32_e32 v0, v0, v1
	v_add_f32_e32 v1, v42, v43
	v_add_f32_e32 v0, v0, v40
	v_add_f32_e32 v0, v0, v1
	ds_bpermute_b32 v1, v26, v0
	s_waitcnt lgkmcnt(0)
	v_add_f32_e32 v0, v0, v1
	ds_bpermute_b32 v1, v27, v0
	s_waitcnt lgkmcnt(0)
	v_add_f32_e32 v0, v0, v1
	ds_bpermute_b32 v1, v28, v0
	s_waitcnt lgkmcnt(0)
	v_add_f32_e32 v0, v0, v1
	ds_bpermute_b32 v1, v29, v0
	s_waitcnt lgkmcnt(0)
	v_add_f32_e32 v0, v0, v1
	ds_bpermute_b32 v1, v30, v0
	s_waitcnt lgkmcnt(0)
	v_add_f32_e32 v0, v0, v1
	ds_bpermute_b32 v1, v31, v0
	s_waitcnt lgkmcnt(0)
	v_add_f32_e32 v0, v0, v1
	v_fmamk_f32 v0, v0, 0x3b2aaaab, v32
	v_mul_f32_e32 v1, 0x4f800000, v0
	v_cmp_gt_f32_e32 vcc, s28, v0
	s_nop 1
	v_cndmask_b32_e32 v40, v0, v1, vcc
	v_sqrt_f32_e32 v41, v40
	v_lshl_add_u64 v[0:1], s[50:51], 0, v[16:17]
	v_add_u32_e32 v42, -1, v41
	v_add_u32_e32 v43, 1, v41
	v_fma_f32 v44, -v42, v41, v40
	v_fma_f32 v45, -v43, v41, v40
	v_cmp_ge_f32_e64 s[8:9], 0, v44
	s_nop 1
	v_cndmask_b32_e64 v41, v41, v42, s[8:9]
	v_cmp_lt_f32_e64 s[8:9], 0, v45
	s_nop 1
	v_cndmask_b32_e64 v41, v41, v43, s[8:9]
	v_mul_f32_e32 v42, 0x37800000, v41
	v_cndmask_b32_e32 v41, v41, v42, vcc
	v_cmp_class_f32_e32 vcc, v40, v33
	s_nop 1
	v_cndmask_b32_e32 v40, v41, v40, vcc
	v_div_scale_f32 v41, s[8:9], v40, v40, 1.0
	v_rcp_f32_e32 v42, v41
	v_add_co_u32_e32 v0, vcc, s29, v0
	s_and_b64 s[8:9], s[26:27], exec
	s_nop 0
	v_addc_co_u32_e32 v1, vcc, 0, v1, vcc
	v_fma_f32 v44, -v41, v42, 1.0
	v_div_scale_f32 v43, vcc, 1.0, v40, 1.0
	v_fmac_f32_e32 v42, v44, v42
	v_mul_f32_e32 v44, v43, v42
	v_fma_f32 v45, -v41, v44, v43
	v_fmac_f32_e32 v44, v45, v42
	v_fma_f32 v41, -v41, v44, v43
	v_div_fmas_f32 v41, v41, v42, v44
	v_div_fixup_f32 v40, v41, v40, 1.0
	v_mul_f32_e32 v2, v2, v40
	v_mul_f32_e32 v3, v3, v40
	v_mul_f32_e32 v2, v38, v2
	v_mul_f32_e32 v3, v39, v3
	v_cvt_pk_bf16_f32 v2, v2, v3
	global_store_dword v[0:1], v2, off
	v_mul_f32_e32 v34, v34, v40
	v_mul_f32_e32 v35, v35, v40
	v_lshl_add_u64 v[38:39], s[50:51], 0, v[20:21]
	s_cselect_b32 s10, s30, 0xc200000
	s_cselect_b32 s23, s19, 0
	s_cselect_b32 s22, s18, s12
	s_waitcnt vmcnt(7) lgkmcnt(0)
	v_mov_b64_e32 v[2:3], v[52:53]
	v_mul_f32_e32 v2, v2, v34
	v_mul_f32_e32 v3, v3, v35
	v_cvt_pk_bf16_f32 v2, v2, v3
	global_store_dword v[0:1], v2, off offset:256
	v_mul_f32_e32 v34, v36, v40
	v_mul_f32_e32 v35, v37, v40
	s_waitcnt vmcnt(7) lgkmcnt(0)
	v_mov_b64_e32 v[2:3], v[54:55]
	v_mul_f32_e32 v2, v2, v34
	v_mul_f32_e32 v3, v3, v35
	v_cvt_pk_bf16_f32 v2, v2, v3
	global_store_dword v[0:1], v2, off offset:512
	s_load_dwordx2 s[24:25], s[0:1], 0xd8
	s_waitcnt lgkmcnt(0)
	s_add_u32 s34, s24, s10
	s_addc_u32 s35, s25, 0
	s_lshl_b64 s[10:11], s[22:23], 10
	s_add_u32 s34, s34, s10
	s_addc_u32 s35, s35, s11
	s_waitcnt vmcnt(6)
	v_mov_b64_e32 v[0:1], v[56:57]
	v_mov_b64_e32 v[2:3], v[58:59]
	v_mov_b64_e32 v[34:35], v[64:65]
	v_mov_b64_e32 v[36:37], v[66:67]
	v_pk_mul_f32 v[38:39], v[2:3], v[2:3]
	v_pk_mul_f32 v[40:41], v[0:1], v[0:1]
	s_nop 0
	v_pk_mov_b32 v[42:43], v[40:41], v[38:39] op_sel:[1,0]
	v_mov_b32_e32 v41, v39
	v_pk_add_f32 v[38:39], v[42:43], v[40:41]
	s_nop 0
	v_add_f32_e32 v38, v38, v39
	ds_bpermute_b32 v39, v26, v38
	s_waitcnt lgkmcnt(0)
	v_add_f32_e32 v38, v38, v39
	ds_bpermute_b32 v39, v27, v38
	s_waitcnt lgkmcnt(0)
	v_add_f32_e32 v38, v38, v39
	ds_bpermute_b32 v39, v28, v38
	s_waitcnt lgkmcnt(0)
	v_add_f32_e32 v38, v38, v39
	ds_bpermute_b32 v39, v29, v38
	s_waitcnt lgkmcnt(0)
	v_add_f32_e32 v38, v38, v39
	ds_bpermute_b32 v39, v30, v38
	s_waitcnt lgkmcnt(0)
	v_add_f32_e32 v38, v38, v39
	ds_bpermute_b32 v39, v31, v38
	s_waitcnt lgkmcnt(0)
	v_add_f32_e32 v38, v38, v39
	v_fmamk_f32 v38, v38, 0x3b800000, v32
	v_mul_f32_e32 v39, 0x4f800000, v38
	v_cmp_gt_f32_e32 vcc, s28, v38
	s_nop 1
	v_cndmask_b32_e32 v38, v38, v39, vcc
	v_sqrt_f32_e32 v39, v38
	s_nop 0
	v_add_u32_e32 v40, -1, v39
	v_add_u32_e32 v41, 1, v39
	v_fma_f32 v42, -v40, v39, v38
	v_fma_f32 v43, -v41, v39, v38
	v_cmp_ge_f32_e64 s[10:11], 0, v42
	s_nop 1
	v_cndmask_b32_e64 v39, v39, v40, s[10:11]
	v_cmp_lt_f32_e64 s[10:11], 0, v43
	s_nop 1
	v_cndmask_b32_e64 v39, v39, v41, s[10:11]
	v_mul_f32_e32 v40, 0x37800000, v39
	v_cndmask_b32_e32 v39, v39, v40, vcc
	v_cmp_class_f32_e32 vcc, v38, v33
	s_nop 1
	v_cndmask_b32_e32 v40, v39, v38, vcc
	v_div_scale_f32 v41, s[10:11], v40, v40, 1.0
	v_rcp_f32_e32 v42, v41
	v_div_scale_f32 v43, vcc, 1.0, v40, 1.0
	v_lshl_add_u64 v[38:39], s[34:35], 0, v[24:25]
	v_fma_f32 v44, -v41, v42, 1.0
	v_fmac_f32_e32 v42, v44, v42
	v_mul_f32_e32 v44, v43, v42
	v_fma_f32 v45, -v41, v44, v43
	v_fmac_f32_e32 v44, v45, v42
	v_fma_f32 v41, -v41, v44, v43
	v_div_fmas_f32 v41, v41, v42, v44
	v_div_fixup_f32 v40, v41, v40, 1.0
	v_pk_mul_f32 v[0:1], v[0:1], v[40:41] op_sel_hi:[1,0]
	v_pk_mul_f32 v[2:3], v[2:3], v[40:41] op_sel_hi:[1,0]
	v_pk_mul_f32 v[0:1], v[34:35], v[0:1]
	v_pk_mul_f32 v[2:3], v[36:37], v[2:3]
	s_mov_b64 vcc, s[8:9]
	global_store_dwordx4 v[38:39], v[0:3], off
	s_cbranch_vccnz .LBB0_2256
	s_lshr_b32 s8, s12, 6
	s_mulk_i32 s8, 0x440
	s_and_b32 s9, s18, 63
	s_or_b32 s8, s8, s9
	s_add_i32 s12, s8, 0x8400
	s_mov_b64 s[20:21], s[12:13]
.LBB0_2256:
	s_lshl_b64 s[8:9], s[20:21], 9
	v_cvt_pk_bf16_f32 v0, v0, v1
	v_cvt_pk_bf16_f32 v1, v2, v3
	v_lshl_add_u64 v[2:3], v[10:11], 0, s[8:9]
	global_store_dwordx2 v[2:3], v[0:1], off
	s_and_saveexec_b64 s[8:9], s[6:7]
	s_cbranch_execz .LBB0_2253
	s_and_b32 s10, s18, 63
	s_and_b32 s12, s18, 0x1fff
	s_or_b32 s34, s10, 0x400
	s_and_b64 s[10:11], s[26:27], exec
	s_cselect_b32 s10, s12, s34
	v_lshl_add_u64 v[0:1], s[50:51], 0, v[18:19]
	s_lshl_b32 s12, s10, 8
	v_add_co_u32_e32 v0, vcc, 0xe000000, v0
	v_lshl_add_u64 v[2:3], v[12:13], 0, s[12:13]
	s_nop 0
	v_addc_co_u32_e32 v1, vcc, 0, v1, vcc
	s_and_b64 s[10:11], s[26:27], exec
	s_cselect_b32 s10, s31, 0xc400000
	s_add_u32 s12, s24, s10
	s_addc_u32 s24, s25, 0
	s_lshl_b64 s[10:11], s[22:23], 8
	s_add_u32 s10, s12, s10
	s_addc_u32 s11, s24, s11
	v_lshl_add_u64 v[0:1], s[10:11], 0, v[4:5]
	s_lshl_b64 s[20:21], s[20:21], 7
	v_lshl_add_u64 v[2:3], v[14:15], 0, s[20:21]
	s_waitcnt vmcnt(0) lgkmcnt(0)
	v_mov_b64_e32 v[34:35], v[70:71]
	v_mov_b32_e32 v36, v72
	v_mov_b32_e32 v37, v73
	v_mul_f32_e32 v38, v36, v35
	v_mul_f32_e32 v36, v36, v34
	v_fma_f32 v34, v37, v34, -v38
	v_fmac_f32_e32 v36, v37, v35
	global_store_dword v[0:1], v34, off
	global_store_dword v[0:1], v36, off offset:128
	v_bfe_u32 v0, v34, 16, 1
	v_bfe_u32 v1, v36, 16, 1
	v_add3_u32 v0, v34, v0, s33
	v_add3_u32 v1, v36, v1, s33
	global_store_short_d16_hi v[2:3], v0, off
	global_store_short_d16_hi v[2:3], v1, off offset:64
	s_branch .LBB0_2253

	.amdhsa_kernel _Z8mega_fwd4Args
		.amdhsa_group_segment_fixed_size 0
		.amdhsa_private_segment_fixed_size 0
		.amdhsa_kernarg_size 496
		.amdhsa_user_sgpr_count 2
		.amdhsa_user_sgpr_dispatch_ptr 0
		.amdhsa_user_sgpr_queue_ptr 0
		.amdhsa_user_sgpr_kernarg_segment_ptr 1
		.amdhsa_user_sgpr_dispatch_id 0
		.amdhsa_user_sgpr_kernarg_preload_length 0
		.amdhsa_user_sgpr_kernarg_preload_offset 0
		.amdhsa_user_sgpr_private_segment_size 0
		.amdhsa_uses_dynamic_stack 0
		.amdhsa_enable_private_segment 0
		.amdhsa_system_sgpr_workgroup_id_x 1
		.amdhsa_system_sgpr_workgroup_id_y 0
		.amdhsa_system_sgpr_workgroup_id_z 0
		.amdhsa_system_sgpr_workgroup_info 0
		.amdhsa_system_vgpr_workitem_id 2
		.amdhsa_next_free_vgpr 247
		.amdhsa_next_free_sgpr 102
		.amdhsa_accum_offset 248
		.amdhsa_reserve_vcc 1
		.amdhsa_float_round_mode_32 0
		.amdhsa_float_round_mode_16_64 0
		.amdhsa_float_denorm_mode_32 3
		.amdhsa_float_denorm_mode_16_64 3
		.amdhsa_dx10_clamp 1
		.amdhsa_ieee_mode 1
		.amdhsa_fp16_overflow 0
		.amdhsa_tg_split 0
		.amdhsa_exception_fp_ieee_invalid_op 0
		.amdhsa_exception_fp_denorm_src 0
		.amdhsa_exception_fp_ieee_div_zero 0
		.amdhsa_exception_fp_ieee_overflow 0
		.amdhsa_exception_fp_ieee_underflow 0
		.amdhsa_exception_fp_ieee_inexact 0
		.amdhsa_exception_int_div_zero 0
	.end_amdhsa_kernel

amdhsa.kernels:
  - .agpr_count:     0
    .args:
      - .offset:         0
        .size:           240
        .value_kind:     by_value
      - .offset:         240
        .size:           4
        .value_kind:     hidden_block_count_x
      - .offset:         244
        .size:           4
        .value_kind:     hidden_block_count_y
      - .offset:         248
        .size:           4
        .value_kind:     hidden_block_count_z
      - .offset:         252
        .size:           2
        .value_kind:     hidden_group_size_x
      - .offset:         254
        .size:           2
        .value_kind:     hidden_group_size_y
      - .offset:         256
        .size:           2
        .value_kind:     hidden_group_size_z
      - .offset:         258
        .size:           2
        .value_kind:     hidden_remainder_x
      - .offset:         260
        .size:           2
        .value_kind:     hidden_remainder_y
      - .offset:         262
        .size:           2
        .value_kind:     hidden_remainder_z
      - .offset:         280
        .size:           8
        .value_kind:     hidden_global_offset_x
      - .offset:         288
        .size:           8
        .value_kind:     hidden_global_offset_y
      - .offset:         296
        .size:           8
        .value_kind:     hidden_global_offset_z
      - .offset:         304
        .size:           2
        .value_kind:     hidden_grid_dims
      - .offset:         328
        .size:           8
        .value_kind:     hidden_multigrid_sync_arg
      - .offset:         360
        .size:           4
        .value_kind:     hidden_dynamic_lds_size
    .group_segment_fixed_size: 0
    .kernarg_segment_align: 8
    .kernarg_segment_size: 496
    .language:       OpenCL C
    .language_version:
      - 2
      - 0
    .max_flat_workgroup_size: 512
    .name:           _Z8mega_fwd4Args
    .private_segment_fixed_size: 0
    .sgpr_count:     108
    .sgpr_spill_count: 5
    .symbol:         _Z8mega_fwd4Args.kd
    .uniform_work_group_size: 1
    .uses_dynamic_stack: false
    .vgpr_count:     247
    .vgpr_spill_count: 0
    .wavefront_size: 64
